# fold finalize into scan3: group-norm/bonus/gate epilogue on the MFMA accumulators, attention rms-norm on the two idle waves, finalize phase and its grid barrier removed
# speedup vs baseline: 1.0255x; 1.0255x over previous
; template <bool COOP>
; __global__ void __launch_bounds__(NTHREADS, 2) mega(Params p0) {
;     ...
;     for (int ph0 = p0.ph_lo * 2; ph0 < p0.ph_hi * 2; ++ph0) {
;         const int ph = ph0 >> 1;
;         const int kind = (ph == 0) ? 9 : (ph == NPHASE - 1 ? 10 : (ph - 1) % 9);
;         const bool rep = ((MK_REP_MASK >> kind) & 1) != 0;
;         if ((ph0 & 1) && !rep) continue;
;         Params p = p0; Lt lt; lt.tid = threadIdx.x; lt.bid = blockIdx.x;
;         asm volatile("" : "+v"(lt.tid)); asm volatile("" : "+s"(lt.bid));
;         { size_t z = 0; asm volatile("" : "+s"(z)); p.ws = p0.ws + z; }
;         unsigned char* ws = p.ws;
;         if (ph == 0) { if (SEL(0)) phase_prep(p, lt, lds); }
;         else if (ph == NPHASE - 1) { if (SEL(1)) phase_final_norm(p, lt); }
;         else {
;             const int l = (ph - 1) / 9, k = (ph - 1) % 9;
.LBB0_11:
	s_bitcmp1_b32 s82, 0
	s_cselect_b64 s[0:1], -1, 0
	s_and_b64 vcc, exec, s[0:1]
	s_cbranch_vccnz .LBB0_10
	s_lshr_b32 s0, s82, 1
	s_cmp_eq_u32 s0, 6
	s_cbranch_scc1 .LBB0_10
	s_cmp_eq_u32 s0, 15
	s_cbranch_scc1 .LBB0_10
	s_cmp_eq_u32 s0, 24
	s_cbranch_scc1 .LBB0_10
	s_cmp_eq_u32 s0, 33
	s_cbranch_scc1 .LBB0_10
	v_mov_b32_e32 v245, v238
	s_mov_b64 s[0:1], 0
	s_ashr_i32 s60, s82, 1
	s_mov_b32 s97, s86
	s_add_u32 s62, s80, s0
	v_writelane_b32 v253, s0, 60
	s_addc_u32 s63, s81, s1
	s_movk_i32 s85, 0x300
	v_writelane_b32 v253, s1, 61
	v_writelane_b32 v253, s60, 62
	s_cmp_gt_u32 s82, 1
	s_mov_b64 s[0:1], -1
	v_writelane_b32 v253, s62, 63
	s_nop 1
	v_writelane_b32 v254, s63, 0
	s_cbranch_scc0 .LBB0_470
	s_cmp_lg_u32 s60, 37
	s_cbranch_scc0 .LBB0_465
	s_add_i32 s0, s60, -1
	s_mul_hi_i32 s1, s0, 0x38e38e39
	s_lshr_b32 s4, s1, 31
	s_ashr_i32 s1, s1, 1
	s_add_i32 s6, s1, s4
	s_mov_b32 s4, s6
	v_writelane_b32 v254, s4, 1
	s_mul_i32 s1, s6, 9
	s_mov_b64 s[6:7], 0
	v_writelane_b32 v254, s5, 2
	s_sub_i32 s4, s0, s1
	v_writelane_b32 v254, s4, 3
	s_cmp_lt_i32 s4, 4
	s_mov_b64 s[4:5], 0
	v_writelane_b32 v254, s4, 4
	s_mov_b64 s[0:1], -1
	s_nop 0
	v_writelane_b32 v254, s5, 5
	s_cbranch_scc1 .LBB0_141
	v_readlane_b32 s0, v254, 3
	s_cmp_gt_i32 s0, 5
	s_cbranch_scc0 .LBB0_88
	s_cmp_gt_i32 s0, 6
	s_cbranch_scc0 .LBB0_89
	s_cmp_eq_u32 s0, 7
	s_mov_b64 s[0:1], -1
	s_cbranch_scc0 .LBB0_87
	s_cmpk_lt_i32 s86, 0x400
	s_cselect_b64 s[0:1], -1, 0
	s_cmpk_gt_i32 s86, 0x3ff
	v_readfirstlane_b32 s10, v245
	s_cbranch_scc1 .LBB0_24
	s_ashr_i32 s4, s86, 31
	s_lshr_b32 s4, s4, 29
	s_add_i32 s8, s86, s4
	s_and_b32 s4, s8, -8
	s_sub_i32 s9, s86, s4
	s_cmp_gt_i32 s9, -1
	s_mov_b64 s[4:5], -1
	s_cbranch_scc0 .LBB0_21
	s_lshl_b32 s28, s9, 7
	s_mov_b64 s[4:5], 0

; __device__ __forceinline__ void phase_finalize(const Params& p, const Lt& lt, int l) {
;     const int tid = lt.tid, lane = tid & 63, w = tid >> 6;
;     const float* yraw = (const float*)(p.ws + WS_YRAW); const float* oraw = (const float*)(p.ws + WS_ORAW); const unsigned char* opnd = p.ws + WS_OPND;
;     const float* gate = (const float*)(p.ws + WS_GATE); const float* bonus = (const float*)(p.ws + WS_BONUS); const float* ssqa = (const float*)(p.ws + WS_SSQA);
;     const float* lg = p.in[12] + l * RW; const float* lb = p.in[13] + l * RW; const float* ang = p.in[15] + l * RW;
;     bf16_t* mix = (bf16_t*)(p.ws + WS_MIX);
;     for (int t = lt.bid * 8 + w; t < SEQ; t += gridDim.x * 8) {
;         const f32x4 sq = *(const f32x4*)(ssqa + (size_t)t * 4);
;         const float ra = rsqrtf((sq[0] + sq[1] + sq[2] + sq[3]) * (1.0f / RW) + NORM_EPS);
; #pragma unroll
;         for (int rnd = 0; rnd < 3; ++rnd) {
;             const int c = rnd * 256 + lane * 4, h = c >> 6, cc = c & 63;
;             const f32x4 y = *(const f32x4*)(yraw + (size_t)t * RW + c);
;             const float m = row16_sum(y[0] + y[1] + y[2] + y[3]) * (1.0f / 64);
;             const f32x4 d = y - m;
;             const float var = row16_sum(d[0] * d[0] + d[1] * d[1] + d[2] * d[2] + d[3] * d[3]) * (1.0f / 64);
;             const float rs = rsqrtf(var + GN_EPS);
;             const f32x4 g4 = *(const f32x4*)(lg + c), b4 = *(const f32x4*)(lb + c), v4 = ld_bf4((const bf16_t*)(opnd + (size_t)t * OPTB + h * OPB + 640 + cc * 2)), gt = ld_bf4((const bf16_t*)gate + (size_t)t * RW + c);
;             const float bo = bonus[(size_t)t * 16 + h];
;             const f32x4 o = (d * rs * g4 + b4 + v4 * bo) * gt;
;             u32x2 pk; pk.x = cvt_pk_bf16(o[0], o[1]); pk.y = cvt_pk_bf16(o[2], o[3]);
;             *(u32x2*)(mix + (size_t)t * DM + c) = pk;
;             const f32x4 oa = *(const f32x4*)(oraw + (size_t)t * RW + c) * ra * *(const f32x4*)(ang + c);
;             u32x2 pa; pa.x = cvt_pk_bf16(oa[0], oa[1]); pa.y = cvt_pk_bf16(oa[2], oa[3]);
;             *(u32x2*)(mix + (size_t)t * DM + RW + c) = pa;
;         }
;     }
; }
; template <bool COOP>
; __global__ void __launch_bounds__(NTHREADS, 2) mega(Params p0) {
;     ...
;             else if (k == 4) { if (SEL(8)) phase_scan3(p, lt, lds); }
;             else if (k == 5) { if (SEL(9)) phase_finalize(p, lt, l); }
.LBB0_129:
	v_readlane_b32 s0, v254, 3
	s_cmp_gt_i32 s0, 4
	s_mov_b64 s[0:1], -1
	s_cbranch_scc0 .LBB0_134
	s_branch .LBB0_140

; __device__ __forceinline__ unsigned cvt_pk_bf16(float lo, float hi) { const f32x2 v = {lo, hi}; return __builtin_bit_cast(unsigned, __builtin_convertvector(v, bf16x2_t)); }
; __device__ __forceinline__ void phase_scan3(const Params& p, const Lt& lt, unsigned char* lds) {
;     ...
;     for (int it = w * G + lt.bid; it < NH * NSEG; it += 8 * G) {
;         int lane = tid & 63; asm volatile("" : "+v"(lane));
;         const int h = it / NSEG, g = it % NSEG, fi = lane & 15, fq = lane >> 4;
;         const float* zb = Z + (size_t)(g * SEGLEN + fi) * RW + h * 64 + fq;
;         const float* sb = SS + (size_t)(h * NSEG + g) * 4096 + (size_t)fi * 64 + fq;
;         float* yb = yraw + (size_t)(g * SEGLEN + 4 * fq) * RW + h * 64 + fi;
;         float bv[4][16];
; #pragma unroll
;         for (int ti = 0; ti < 4; ++ti)
; #pragma unroll
;             for (int ks = 0; ks < 16; ++ks) bv[ti][ks] = sb[(size_t)ti * 16 * 64 + 4 * ks];
; #pragma unroll 1
;         for (int tt = 0; tt < 4; ++tt) {
;             float av[16];
; #pragma unroll
;             for (int ks = 0; ks < 16; ++ks) av[ks] = zb[(size_t)tt * 16 * RW + 4 * ks];
;             f32x4 acc[4];
; #pragma unroll
;             for (int ti = 0; ti < 4; ++ti)
; #pragma unroll
;                 for (int r = 0; r < 4; ++r) acc[ti][r] = yb[(size_t)(tt * 16 + r) * RW + ti * 16];
; __device__ __forceinline__ void phase_finalize(const Params& p, const Lt& lt, int l) {
;     ...
;             const f32x4 y = *(const f32x4*)(yraw + (size_t)t * RW + c);
;             const float m = row16_sum(y[0] + y[1] + y[2] + y[3]) * (1.0f / 64);
;             const f32x4 d = y - m;
;             const float var = row16_sum(d[0] * d[0] + d[1] * d[1] + d[2] * d[2] + d[3] * d[3]) * (1.0f / 64);
;             const float rs = rsqrtf(var + GN_EPS);
;             const f32x4 g4 = *(const f32x4*)(lg + c), b4 = *(const f32x4*)(lb + c), v4 = ld_bf4((const bf16_t*)(opnd + (size_t)t * OPTB + h * OPB + 640 + cc * 2)), gt = ld_bf4((const bf16_t*)gate + (size_t)t * RW + c);
;             const float bo = bonus[(size_t)t * 16 + h];
;             const f32x4 o = (d * rs * g4 + b4 + v4 * bo) * gt;
;             u32x2 pk; pk.x = cvt_pk_bf16(o[0], o[1]); pk.y = cvt_pk_bf16(o[2], o[3]);
;             *(u32x2*)(mix + (size_t)t * DM + c) = pk;
.LBB0_137:
	v_and_b32_e32 v0, 15, v14
	v_lshrrev_b32_e32 v1, 4, v14
	s_lshr_b32 s1, s0, 7
	s_and_b32 s10, s0, 0x7f
	s_lshl_b32 s4, s0, 14
	s_add_u32 s50, s8, s4
	s_addc_u32 s51, s9, 0
	s_mul_i32 s4, s10, 0x30000
	s_lshl_b32 s5, s1, 8
	s_add_u32 s4, s4, s5
	s_add_u32 s48, s62, 0x32fa0000
	s_addc_u32 s49, s63, 0
	s_add_u32 s48, s48, s4
	s_addc_u32 s49, s49, 0
	s_add_u32 s28, s62, 0x2a780000
	s_addc_u32 s29, s63, 0
	s_add_u32 s28, s28, s4
	s_addc_u32 s29, s29, 0
	s_add_u32 s30, s28, 0x1800
	s_addc_u32 s31, s29, 0
	s_mul_i32 s4, s10, 0xa8000
	s_mul_i32 s5, s1, 0x380
	s_add_u32 s4, s4, s5
	s_add_u32 s4, s4, 0x280
	s_add_u32 s34, s62, 0x23b00000
	s_addc_u32 s35, s63, 0
	s_add_u32 s34, s34, s4
	s_addc_u32 s35, s35, 0
	s_mul_i32 s4, s10, 0x18000
	s_lshl_b32 s5, s1, 7
	s_add_u32 s4, s4, s5
	s_add_u32 s36, s62, 0x28f00000
	s_addc_u32 s37, s63, 0
	s_add_u32 s36, s36, s4
	s_addc_u32 s37, s37, 0
	s_add_u32 s38, s36, 0xc00
	s_addc_u32 s39, s37, 0
	s_lshl_b32 s4, s10, 12
	s_lshl_b32 s5, s1, 2
	s_add_u32 s4, s4, s5
	s_add_u32 s40, s62, 0x2a700000
	s_addc_u32 s41, s63, 0
	s_add_u32 s40, s40, s4
	s_addc_u32 s41, s41, 0
	s_lshl_b32 s4, s10, 18
	s_lshl_b32 s5, s1, 7
	s_add_u32 s4, s4, s5
	s_add_u32 s42, s62, 0x1cf00000
	s_addc_u32 s43, s63, 0
	s_add_u32 s42, s42, s4
	s_addc_u32 s43, s43, 0
	v_readlane_b32 s4, v254, 1
	s_mul_i32 s4, s4, 0xc00
	s_lshl_b32 s5, s1, 8
	s_add_u32 s4, s4, s5
	v_readlane_b32 s44, v253, 35
	v_readlane_b32 s45, v253, 36
	s_add_u32 s44, s44, s4
	s_addc_u32 s45, s45, 0
	v_readlane_b32 s46, v253, 37
	v_readlane_b32 s47, v253, 38
	s_add_u32 s46, s46, s4
	s_addc_u32 s47, s47, 0
	v_lshlrev_b32_e32 v248, 4, v0
	v_lshlrev_b32_e32 v145, 10, v0
	v_lshl_add_u32 v145, v1, 6, v145
	v_mul_u32_u24_e32 v144, 0xc00, v0
	v_lshl_add_u32 v144, v1, 6, v144
	v_mul_u32_u24_e32 v12, 0x3000, v1
	v_lshl_add_u32 v12, v0, 4, v12
	v_mul_u32_u24_e32 v13, 0x1800, v1
	v_lshl_add_u32 v13, v0, 3, v13
	v_lshlrev_b32_e32 v15, 8, v1
	v_lshlrev_b32_e32 v2, 2, v1
	v_add_u32_e32 v192, 0, v2
	v_mul_u32_u24_e32 v192, 0x2a00, v192
	v_lshl_add_u32 v192, v0, 3, v192
	v_add_u32_e32 v193, 1, v2
	v_mul_u32_u24_e32 v193, 0x2a00, v193
	v_lshl_add_u32 v193, v0, 3, v193
	v_add_u32_e32 v194, 2, v2
	v_mul_u32_u24_e32 v194, 0x2a00, v194
	v_lshl_add_u32 v194, v0, 3, v194
	v_add_u32_e32 v195, 3, v2
	v_mul_u32_u24_e32 v195, 0x2a00, v195
	v_lshl_add_u32 v195, v0, 3, v195
	v_lshlrev_b32_e32 v2, 14, v1
	v_lshl_add_u32 v2, v0, 3, v2
	v_mov_b32_e32 v234, v2
	v_add_u32_e32 v235, 0x1000, v2
	v_add_u32_e32 v236, 0x2000, v2
	v_add_u32_e32 v237, 0x3000, v2
	s_nop 0
	global_load_dwordx4 v[4:7], v248, s[44:45]
	global_load_dwordx4 v[8:11], v248, s[46:47]
	global_load_dwordx4 v[16:19], v145, s[50:51] offset:0
	global_load_dwordx4 v[20:23], v145, s[50:51] offset:16
	global_load_dwordx4 v[24:27], v145, s[50:51] offset:32
	global_load_dwordx4 v[28:31], v145, s[50:51] offset:48
	global_load_dwordx4 v[32:35], v145, s[50:51] offset:256
	global_load_dwordx4 v[36:39], v145, s[50:51] offset:272
	global_load_dwordx4 v[40:43], v145, s[50:51] offset:288
	global_load_dwordx4 v[44:47], v145, s[50:51] offset:304
	global_load_dwordx4 v[48:51], v145, s[50:51] offset:512
	global_load_dwordx4 v[52:55], v145, s[50:51] offset:528
	global_load_dwordx4 v[56:59], v145, s[50:51] offset:544
	global_load_dwordx4 v[60:63], v145, s[50:51] offset:560
	global_load_dwordx4 v[64:67], v145, s[50:51] offset:768
	global_load_dwordx4 v[68:71], v145, s[50:51] offset:784
	global_load_dwordx4 v[72:75], v145, s[50:51] offset:800
	global_load_dwordx4 v[76:79], v145, s[50:51] offset:816
	global_load_dwordx4 v[80:83], v144, s[48:49] offset:0
	global_load_dwordx4 v[84:87], v144, s[48:49] offset:16
	global_load_dwordx4 v[88:91], v144, s[48:49] offset:32
	global_load_dwordx4 v[92:95], v144, s[48:49] offset:48
	global_load_dwordx4 v[128:131], v12, s[28:29]
	global_load_dwordx4 v[132:135], v12, s[28:29] offset:3072
	global_load_dwordx4 v[136:139], v12, s[30:31]
	global_load_dwordx4 v[140:143], v12, s[30:31] offset:3072
	global_load_dwordx2 v[176:177], v192, s[34:35]
	global_load_dwordx2 v[178:179], v193, s[34:35]
	global_load_dwordx2 v[180:181], v194, s[34:35]
	global_load_dwordx2 v[182:183], v195, s[34:35]
	global_load_dwordx2 v[210:211], v13, s[36:37]
	global_load_dwordx2 v[212:213], v13, s[36:37] offset:1536
	global_load_dwordx2 v[214:215], v13, s[38:39]
	global_load_dwordx2 v[216:217], v13, s[38:39] offset:1536
	global_load_dword v226, v15, s[40:41]
	global_load_dword v227, v15, s[40:41] offset:64
	global_load_dword v228, v15, s[40:41] offset:128
	global_load_dword v229, v15, s[40:41] offset:192
	s_mov_b32 s52, 0
; __device__ __forceinline__ float row16_sum(float v) { v += __shfl_xor(v, 1); v += __shfl_xor(v, 2); v += __shfl_xor(v, 4); v += __shfl_xor(v, 8); return v; }
; __device__ __forceinline__ void phase_scan3(const Params& p, const Lt& lt, unsigned char* lds) {
;     ...
;             for (int ks = 0; ks < 16; ++ks) av[ks] = zb[(size_t)tt * 16 * RW + 4 * ks];
;             f32x4 acc[4];
; #pragma unroll
;             for (int ti = 0; ti < 4; ++ti)
; #pragma unroll
;                 for (int r = 0; r < 4; ++r) acc[ti][r] = yb[(size_t)(tt * 16 + r) * RW + ti * 16];
; #pragma unroll
;             for (int ks = 0; ks < 16; ++ks)
; #pragma unroll
;                 for (int ti = 0; ti < 4; ++ti) acc[ti] = __builtin_amdgcn_mfma_f32_16x16x4f32(av[ks], bv[ti][ks], acc[ti], 0, 0, 0);
; #pragma unroll
;             for (int ti = 0; ti < 4; ++ti)
; #pragma unroll
;                 for (int r = 0; r < 4; ++r) yb[(size_t)(tt * 16 + r) * RW + ti * 16] = acc[ti][r];
; __device__ __forceinline__ void phase_finalize(const Params& p, const Lt& lt, int l) {
;     ...
;             const f32x4 y = *(const f32x4*)(yraw + (size_t)t * RW + c);
;             const float m = row16_sum(y[0] + y[1] + y[2] + y[3]) * (1.0f / 64);
.Ls3_trip:
	s_add_u32 s48, s48, 0xc000
	s_addc_u32 s49, s49, 0
	s_add_u32 s28, s28, 0xc000
	s_addc_u32 s29, s29, 0
	s_add_u32 s30, s30, 0xc000
	s_addc_u32 s31, s31, 0
	s_add_u32 s34, s34, 0x2a000
	s_addc_u32 s35, s35, 0
	s_add_u32 s36, s36, 0x6000
	s_addc_u32 s37, s37, 0
	s_add_u32 s38, s38, 0x6000
	s_addc_u32 s39, s39, 0
	s_add_u32 s40, s40, 0x400
	s_addc_u32 s41, s41, 0
	global_load_dwordx4 v[96:99], v144, s[48:49] offset:0
	global_load_dwordx4 v[100:103], v144, s[48:49] offset:16
	global_load_dwordx4 v[104:107], v144, s[48:49] offset:32
	global_load_dwordx4 v[108:111], v144, s[48:49] offset:48
	global_load_dwordx4 v[160:163], v12, s[28:29]
	global_load_dwordx4 v[164:167], v12, s[28:29] offset:3072
	global_load_dwordx4 v[168:171], v12, s[30:31]
	global_load_dwordx4 v[172:175], v12, s[30:31] offset:3072
	global_load_dwordx2 v[184:185], v192, s[34:35]
	global_load_dwordx2 v[186:187], v193, s[34:35]
	global_load_dwordx2 v[188:189], v194, s[34:35]
	global_load_dwordx2 v[190:191], v195, s[34:35]
	global_load_dwordx2 v[218:219], v13, s[36:37]
	global_load_dwordx2 v[220:221], v13, s[36:37] offset:1536
	global_load_dwordx2 v[222:223], v13, s[38:39]
	global_load_dwordx2 v[224:225], v13, s[38:39] offset:1536
	global_load_dword v230, v15, s[40:41]
	global_load_dword v231, v15, s[40:41] offset:64
	global_load_dword v232, v15, s[40:41] offset:128
	global_load_dword v233, v15, s[40:41] offset:192
	s_waitcnt vmcnt(20)
	v_mfma_f32_16x16x4_f32 v[112:115], v80, v16, 0
	v_mfma_f32_16x16x4_f32 v[116:119], v80, v32, 0
	v_mfma_f32_16x16x4_f32 v[120:123], v80, v48, 0
	v_mfma_f32_16x16x4_f32 v[124:127], v80, v64, 0
	v_mfma_f32_16x16x4_f32 v[112:115], v81, v17, v[112:115]
	v_mfma_f32_16x16x4_f32 v[116:119], v81, v33, v[116:119]
	v_mfma_f32_16x16x4_f32 v[120:123], v81, v49, v[120:123]
	v_mfma_f32_16x16x4_f32 v[124:127], v81, v65, v[124:127]
	v_mfma_f32_16x16x4_f32 v[112:115], v82, v18, v[112:115]
	v_mfma_f32_16x16x4_f32 v[116:119], v82, v34, v[116:119]
	v_mfma_f32_16x16x4_f32 v[120:123], v82, v50, v[120:123]
	v_mfma_f32_16x16x4_f32 v[124:127], v82, v66, v[124:127]
	v_mfma_f32_16x16x4_f32 v[112:115], v83, v19, v[112:115]
	v_mfma_f32_16x16x4_f32 v[116:119], v83, v35, v[116:119]
	v_mfma_f32_16x16x4_f32 v[120:123], v83, v51, v[120:123]
	v_mfma_f32_16x16x4_f32 v[124:127], v83, v67, v[124:127]
	v_mfma_f32_16x16x4_f32 v[112:115], v84, v20, v[112:115]
	v_mfma_f32_16x16x4_f32 v[116:119], v84, v36, v[116:119]
	v_mfma_f32_16x16x4_f32 v[120:123], v84, v52, v[120:123]
	v_mfma_f32_16x16x4_f32 v[124:127], v84, v68, v[124:127]
	v_mfma_f32_16x16x4_f32 v[112:115], v85, v21, v[112:115]
	v_mfma_f32_16x16x4_f32 v[116:119], v85, v37, v[116:119]
	v_mfma_f32_16x16x4_f32 v[120:123], v85, v53, v[120:123]
	v_mfma_f32_16x16x4_f32 v[124:127], v85, v69, v[124:127]
	v_mfma_f32_16x16x4_f32 v[112:115], v86, v22, v[112:115]
	v_mfma_f32_16x16x4_f32 v[116:119], v86, v38, v[116:119]
	v_mfma_f32_16x16x4_f32 v[120:123], v86, v54, v[120:123]
	v_mfma_f32_16x16x4_f32 v[124:127], v86, v70, v[124:127]
	v_mfma_f32_16x16x4_f32 v[112:115], v87, v23, v[112:115]
	v_mfma_f32_16x16x4_f32 v[116:119], v87, v39, v[116:119]
	v_mfma_f32_16x16x4_f32 v[120:123], v87, v55, v[120:123]
	v_mfma_f32_16x16x4_f32 v[124:127], v87, v71, v[124:127]
	v_mfma_f32_16x16x4_f32 v[112:115], v88, v24, v[112:115]
	v_mfma_f32_16x16x4_f32 v[116:119], v88, v40, v[116:119]
	v_mfma_f32_16x16x4_f32 v[120:123], v88, v56, v[120:123]
	v_mfma_f32_16x16x4_f32 v[124:127], v88, v72, v[124:127]
	v_mfma_f32_16x16x4_f32 v[112:115], v89, v25, v[112:115]
	v_mfma_f32_16x16x4_f32 v[116:119], v89, v41, v[116:119]
	v_mfma_f32_16x16x4_f32 v[120:123], v89, v57, v[120:123]
	v_mfma_f32_16x16x4_f32 v[124:127], v89, v73, v[124:127]
	v_mfma_f32_16x16x4_f32 v[112:115], v90, v26, v[112:115]
	v_mfma_f32_16x16x4_f32 v[116:119], v90, v42, v[116:119]
	v_mfma_f32_16x16x4_f32 v[120:123], v90, v58, v[120:123]
	v_mfma_f32_16x16x4_f32 v[124:127], v90, v74, v[124:127]
	v_mfma_f32_16x16x4_f32 v[112:115], v91, v27, v[112:115]
	v_mfma_f32_16x16x4_f32 v[116:119], v91, v43, v[116:119]
	v_mfma_f32_16x16x4_f32 v[120:123], v91, v59, v[120:123]
	v_mfma_f32_16x16x4_f32 v[124:127], v91, v75, v[124:127]
	v_mfma_f32_16x16x4_f32 v[112:115], v92, v28, v[112:115]
	v_mfma_f32_16x16x4_f32 v[116:119], v92, v44, v[116:119]
	v_mfma_f32_16x16x4_f32 v[120:123], v92, v60, v[120:123]
	v_mfma_f32_16x16x4_f32 v[124:127], v92, v76, v[124:127]
	v_mfma_f32_16x16x4_f32 v[112:115], v93, v29, v[112:115]
	v_mfma_f32_16x16x4_f32 v[116:119], v93, v45, v[116:119]
	v_mfma_f32_16x16x4_f32 v[120:123], v93, v61, v[120:123]
	v_mfma_f32_16x16x4_f32 v[124:127], v93, v77, v[124:127]
	v_mfma_f32_16x16x4_f32 v[112:115], v94, v30, v[112:115]
	v_mfma_f32_16x16x4_f32 v[116:119], v94, v46, v[116:119]
	v_mfma_f32_16x16x4_f32 v[120:123], v94, v62, v[120:123]
	v_mfma_f32_16x16x4_f32 v[124:127], v94, v78, v[124:127]
	v_mfma_f32_16x16x4_f32 v[112:115], v95, v31, v[112:115]
	v_mfma_f32_16x16x4_f32 v[116:119], v95, v47, v[116:119]
	v_mfma_f32_16x16x4_f32 v[120:123], v95, v63, v[120:123]
	v_mfma_f32_16x16x4_f32 v[124:127], v95, v79, v[124:127]
	s_nop 9
	v_add_f32_e32 v128, v112, v128
	v_add_f32_e32 v129, v116, v129
	v_add_f32_e32 v130, v120, v130
	v_add_f32_e32 v131, v124, v131
	v_add_f32_e32 v132, v113, v132
	v_add_f32_e32 v133, v117, v133
	v_add_f32_e32 v134, v121, v134
	v_add_f32_e32 v135, v125, v135
	v_add_f32_e32 v136, v114, v136
	v_add_f32_e32 v137, v118, v137
	v_add_f32_e32 v138, v122, v138
	v_add_f32_e32 v139, v126, v139
	v_add_f32_e32 v140, v115, v140
	v_add_f32_e32 v141, v119, v141
	v_add_f32_e32 v142, v123, v142
	v_add_f32_e32 v143, v127, v143
	v_add_f32_e32 v146, v128, v129
	v_add_f32_e32 v147, v132, v133
; __device__ __forceinline__ float row16_sum(float v) { v += __shfl_xor(v, 1); v += __shfl_xor(v, 2); v += __shfl_xor(v, 4); v += __shfl_xor(v, 8); return v; }
; __device__ __forceinline__ f32x4 ld_bf4(const bf16_t* q) { const u32x2 u = *(const u32x2*)q; return (f32x4){bflo(u.x), bfhi(u.x), bflo(u.y), bfhi(u.y)}; }
; __device__ __forceinline__ void phase_finalize(const Params& p, const Lt& lt, int l) {
;     ...
;             const f32x4 y = *(const f32x4*)(yraw + (size_t)t * RW + c);
;             const float m = row16_sum(y[0] + y[1] + y[2] + y[3]) * (1.0f / 64);
;             const f32x4 d = y - m;
;             const float var = row16_sum(d[0] * d[0] + d[1] * d[1] + d[2] * d[2] + d[3] * d[3]) * (1.0f / 64);
;             const float rs = rsqrtf(var + GN_EPS);
;             const f32x4 g4 = *(const f32x4*)(lg + c), b4 = *(const f32x4*)(lb + c), v4 = ld_bf4((const bf16_t*)(opnd + (size_t)t * OPTB + h * OPB + 640 + cc * 2)), gt = ld_bf4((const bf16_t*)gate + (size_t)t * RW + c);
;             const float bo = bonus[(size_t)t * 16 + h];
;             const f32x4 o = (d * rs * g4 + b4 + v4 * bo) * gt;
	v_add_f32_e32 v148, v136, v137
	v_add_f32_e32 v149, v140, v141
	v_add_f32_e32 v146, v130, v146
	v_add_f32_e32 v147, v134, v147
	v_add_f32_e32 v148, v138, v148
	v_add_f32_e32 v149, v142, v149
	v_add_f32_e32 v146, v131, v146
	v_add_f32_e32 v147, v135, v147
	v_add_f32_e32 v148, v139, v148
	v_add_f32_e32 v149, v143, v149
	v_add_f32_dpp v146, v146, v146 quad_perm:[1,0,3,2] row_mask:0xf bank_mask:0xf
	v_add_f32_dpp v147, v147, v147 quad_perm:[1,0,3,2] row_mask:0xf bank_mask:0xf
	v_add_f32_dpp v148, v148, v148 quad_perm:[1,0,3,2] row_mask:0xf bank_mask:0xf
	v_add_f32_dpp v149, v149, v149 quad_perm:[1,0,3,2] row_mask:0xf bank_mask:0xf
	v_add_f32_dpp v146, v146, v146 quad_perm:[2,3,0,1] row_mask:0xf bank_mask:0xf
	v_add_f32_dpp v147, v147, v147 quad_perm:[2,3,0,1] row_mask:0xf bank_mask:0xf
	v_add_f32_dpp v148, v148, v148 quad_perm:[2,3,0,1] row_mask:0xf bank_mask:0xf
	v_add_f32_dpp v149, v149, v149 quad_perm:[2,3,0,1] row_mask:0xf bank_mask:0xf
	v_add_f32_dpp v146, v146, v146 row_half_mirror row_mask:0xf bank_mask:0xf
	v_add_f32_dpp v147, v147, v147 row_half_mirror row_mask:0xf bank_mask:0xf
	v_add_f32_dpp v148, v148, v148 row_half_mirror row_mask:0xf bank_mask:0xf
	v_add_f32_dpp v149, v149, v149 row_half_mirror row_mask:0xf bank_mask:0xf
	v_add_f32_dpp v146, v146, v146 row_mirror row_mask:0xf bank_mask:0xf
	v_add_f32_dpp v147, v147, v147 row_mirror row_mask:0xf bank_mask:0xf
	v_add_f32_dpp v148, v148, v148 row_mirror row_mask:0xf bank_mask:0xf
	v_add_f32_dpp v149, v149, v149 row_mirror row_mask:0xf bank_mask:0xf
	v_fmamk_f32 v128, v146, 0xbc800000, v128
	v_fmamk_f32 v129, v146, 0xbc800000, v129
	v_fmamk_f32 v130, v146, 0xbc800000, v130
	v_fmamk_f32 v131, v146, 0xbc800000, v131
	v_fmamk_f32 v132, v147, 0xbc800000, v132
	v_fmamk_f32 v133, v147, 0xbc800000, v133
	v_fmamk_f32 v134, v147, 0xbc800000, v134
	v_fmamk_f32 v135, v147, 0xbc800000, v135
	v_fmamk_f32 v136, v148, 0xbc800000, v136
	v_fmamk_f32 v137, v148, 0xbc800000, v137
	v_fmamk_f32 v138, v148, 0xbc800000, v138
	v_fmamk_f32 v139, v148, 0xbc800000, v139
	v_fmamk_f32 v140, v149, 0xbc800000, v140
	v_fmamk_f32 v141, v149, 0xbc800000, v141
	v_fmamk_f32 v142, v149, 0xbc800000, v142
	v_fmamk_f32 v143, v149, 0xbc800000, v143
	v_mul_f32_e32 v154, v128, v128
	v_mul_f32_e32 v155, v129, v129
	v_mul_f32_e32 v156, v132, v132
	v_mul_f32_e32 v157, v133, v133
	v_mul_f32_e32 v158, v136, v136
	v_mul_f32_e32 v159, v137, v137
	v_mul_f32_e32 v198, v140, v140
	v_mul_f32_e32 v199, v141, v141
	v_add_f32_e32 v150, v154, v155
	v_add_f32_e32 v151, v156, v157
	v_add_f32_e32 v152, v158, v159
	v_add_f32_e32 v153, v198, v199
	v_mul_f32_e32 v154, v130, v130
	v_mul_f32_e32 v156, v134, v134
	v_mul_f32_e32 v158, v138, v138
	v_mul_f32_e32 v198, v142, v142
	v_mul_f32_e32 v155, v131, v131
	v_mul_f32_e32 v157, v135, v135
	v_mul_f32_e32 v159, v139, v139
	v_mul_f32_e32 v199, v143, v143
	v_add_f32_e32 v150, v154, v150
	v_add_f32_e32 v151, v156, v151
	v_add_f32_e32 v152, v158, v152
	v_add_f32_e32 v153, v198, v153
	v_add_f32_e32 v150, v155, v150
	v_add_f32_e32 v151, v157, v151
	v_add_f32_e32 v152, v159, v152
	v_add_f32_e32 v153, v199, v153
	v_add_f32_dpp v150, v150, v150 quad_perm:[1,0,3,2] row_mask:0xf bank_mask:0xf
	v_add_f32_dpp v151, v151, v151 quad_perm:[1,0,3,2] row_mask:0xf bank_mask:0xf
	v_add_f32_dpp v152, v152, v152 quad_perm:[1,0,3,2] row_mask:0xf bank_mask:0xf
	v_add_f32_dpp v153, v153, v153 quad_perm:[1,0,3,2] row_mask:0xf bank_mask:0xf
	v_add_f32_dpp v150, v150, v150 quad_perm:[2,3,0,1] row_mask:0xf bank_mask:0xf
	v_add_f32_dpp v151, v151, v151 quad_perm:[2,3,0,1] row_mask:0xf bank_mask:0xf
	v_add_f32_dpp v152, v152, v152 quad_perm:[2,3,0,1] row_mask:0xf bank_mask:0xf
	v_add_f32_dpp v153, v153, v153 quad_perm:[2,3,0,1] row_mask:0xf bank_mask:0xf
	v_add_f32_dpp v150, v150, v150 row_half_mirror row_mask:0xf bank_mask:0xf
	v_add_f32_dpp v151, v151, v151 row_half_mirror row_mask:0xf bank_mask:0xf
	v_add_f32_dpp v152, v152, v152 row_half_mirror row_mask:0xf bank_mask:0xf
	v_add_f32_dpp v153, v153, v153 row_half_mirror row_mask:0xf bank_mask:0xf
	v_add_f32_dpp v150, v150, v150 row_mirror row_mask:0xf bank_mask:0xf
	v_add_f32_dpp v151, v151, v151 row_mirror row_mask:0xf bank_mask:0xf
	v_add_f32_dpp v152, v152, v152 row_mirror row_mask:0xf bank_mask:0xf
	v_add_f32_dpp v153, v153, v153 row_mirror row_mask:0xf bank_mask:0xf
	v_fmamk_f32 v150, v150, 0x3c800000, v196
	v_fmamk_f32 v151, v151, 0x3c800000, v196
	v_fmamk_f32 v152, v152, 0x3c800000, v196
	v_fmamk_f32 v153, v153, 0x3c800000, v196
	v_rsq_f32_e32 v150, v150
	v_rsq_f32_e32 v151, v151
	v_rsq_f32_e32 v152, v152
	v_rsq_f32_e32 v153, v153
	s_nop 0
	v_mul_f32_e32 v128, v128, v150
	v_mul_f32_e32 v129, v129, v150
	v_mul_f32_e32 v130, v130, v150
	v_mul_f32_e32 v131, v131, v150
	v_mul_f32_e32 v132, v132, v151
	v_mul_f32_e32 v133, v133, v151
	v_mul_f32_e32 v134, v134, v151
	v_mul_f32_e32 v135, v135, v151
	v_mul_f32_e32 v136, v136, v152
	v_mul_f32_e32 v137, v137, v152
	v_mul_f32_e32 v138, v138, v152
	v_mul_f32_e32 v139, v139, v152
	v_mul_f32_e32 v140, v140, v153
	v_mul_f32_e32 v141, v141, v153
	v_mul_f32_e32 v142, v142, v153
	v_mul_f32_e32 v143, v143, v153
	v_fma_f32 v128, v4, v128, v8
	v_fma_f32 v129, v5, v129, v9
	v_fma_f32 v130, v6, v130, v10
	v_fma_f32 v131, v7, v131, v11
	v_fma_f32 v132, v4, v132, v8
	v_fma_f32 v133, v5, v133, v9
	v_fma_f32 v134, v6, v134, v10
	v_fma_f32 v135, v7, v135, v11
	v_fma_f32 v136, v4, v136, v8
	v_fma_f32 v137, v5, v137, v9
	v_fma_f32 v138, v6, v138, v10
	v_fma_f32 v139, v7, v139, v11
	v_fma_f32 v140, v4, v140, v8
	v_fma_f32 v141, v5, v141, v9
	v_fma_f32 v142, v6, v142, v10
	v_fma_f32 v143, v7, v143, v11
	v_lshlrev_b32_e32 v154, 16, v176
; __device__ __forceinline__ unsigned cvt_pk_bf16(float lo, float hi) { const f32x2 v = {lo, hi}; return __builtin_bit_cast(unsigned, __builtin_convertvector(v, bf16x2_t)); }
; __device__ __forceinline__ f32x4 ld_bf4(const bf16_t* q) { const u32x2 u = *(const u32x2*)q; return (f32x4){bflo(u.x), bfhi(u.x), bflo(u.y), bfhi(u.y)}; }
; __device__ __forceinline__ void phase_scan3(const Params& p, const Lt& lt, unsigned char* lds) {
;     ...
;             for (int ks = 0; ks < 16; ++ks) av[ks] = zb[(size_t)tt * 16 * RW + 4 * ks];
;             f32x4 acc[4];
; #pragma unroll
;             for (int ti = 0; ti < 4; ++ti)
; #pragma unroll
;                 for (int r = 0; r < 4; ++r) acc[ti][r] = yb[(size_t)(tt * 16 + r) * RW + ti * 16];
; #pragma unroll
;             for (int ks = 0; ks < 16; ++ks)
; #pragma unroll
;                 for (int ti = 0; ti < 4; ++ti) acc[ti] = __builtin_amdgcn_mfma_f32_16x16x4f32(av[ks], bv[ti][ks], acc[ti], 0, 0, 0);
; __device__ __forceinline__ void phase_finalize(const Params& p, const Lt& lt, int l) {
;     ...
;             const f32x4 g4 = *(const f32x4*)(lg + c), b4 = *(const f32x4*)(lb + c), v4 = ld_bf4((const bf16_t*)(opnd + (size_t)t * OPTB + h * OPB + 640 + cc * 2)), gt = ld_bf4((const bf16_t*)gate + (size_t)t * RW + c);
;             const float bo = bonus[(size_t)t * 16 + h];
;             const f32x4 o = (d * rs * g4 + b4 + v4 * bo) * gt;
;             u32x2 pk; pk.x = cvt_pk_bf16(o[0], o[1]); pk.y = cvt_pk_bf16(o[2], o[3]);
;             *(u32x2*)(mix + (size_t)t * DM + c) = pk;
	v_and_b32_e32 v155, 0xffff0000, v176
	v_lshlrev_b32_e32 v156, 16, v177
	v_and_b32_e32 v157, 0xffff0000, v177
	v_fma_f32 v128, v226, v154, v128
	v_fma_f32 v129, v226, v155, v129
	v_fma_f32 v130, v226, v156, v130
	v_fma_f32 v131, v226, v157, v131
	v_lshlrev_b32_e32 v158, 16, v178
	v_and_b32_e32 v159, 0xffff0000, v178
	v_lshlrev_b32_e32 v198, 16, v179
	v_and_b32_e32 v199, 0xffff0000, v179
	v_fma_f32 v132, v227, v158, v132
	v_fma_f32 v133, v227, v159, v133
	v_fma_f32 v134, v227, v198, v134
	v_fma_f32 v135, v227, v199, v135
	v_lshlrev_b32_e32 v154, 16, v180
	v_and_b32_e32 v155, 0xffff0000, v180
	v_lshlrev_b32_e32 v156, 16, v181
	v_and_b32_e32 v157, 0xffff0000, v181
	v_fma_f32 v136, v228, v154, v136
	v_fma_f32 v137, v228, v155, v137
	v_fma_f32 v138, v228, v156, v138
	v_fma_f32 v139, v228, v157, v139
	v_lshlrev_b32_e32 v158, 16, v182
	v_and_b32_e32 v159, 0xffff0000, v182
	v_lshlrev_b32_e32 v198, 16, v183
	v_and_b32_e32 v199, 0xffff0000, v183
	v_fma_f32 v140, v229, v158, v140
	v_fma_f32 v141, v229, v159, v141
	v_fma_f32 v142, v229, v198, v142
	v_fma_f32 v143, v229, v199, v143
	v_lshlrev_b32_e32 v154, 16, v210
	v_and_b32_e32 v155, 0xffff0000, v210
	v_lshlrev_b32_e32 v156, 16, v211
	v_and_b32_e32 v157, 0xffff0000, v211
	v_mul_f32_e32 v128, v128, v154
	v_mul_f32_e32 v129, v129, v155
	v_mul_f32_e32 v130, v130, v156
	v_mul_f32_e32 v131, v131, v157
	v_lshlrev_b32_e32 v158, 16, v212
	v_and_b32_e32 v159, 0xffff0000, v212
	v_lshlrev_b32_e32 v198, 16, v213
	v_and_b32_e32 v199, 0xffff0000, v213
	v_mul_f32_e32 v132, v132, v158
	v_mul_f32_e32 v133, v133, v159
	v_mul_f32_e32 v134, v134, v198
	v_mul_f32_e32 v135, v135, v199
	v_lshlrev_b32_e32 v154, 16, v214
	v_and_b32_e32 v155, 0xffff0000, v214
	v_lshlrev_b32_e32 v156, 16, v215
	v_and_b32_e32 v157, 0xffff0000, v215
	v_mul_f32_e32 v136, v136, v154
	v_mul_f32_e32 v137, v137, v155
	v_mul_f32_e32 v138, v138, v156
	v_mul_f32_e32 v139, v139, v157
	v_lshlrev_b32_e32 v158, 16, v216
	v_and_b32_e32 v159, 0xffff0000, v216
	v_lshlrev_b32_e32 v198, 16, v217
	v_and_b32_e32 v199, 0xffff0000, v217
	v_mul_f32_e32 v140, v140, v158
	v_mul_f32_e32 v141, v141, v159
	v_mul_f32_e32 v142, v142, v198
	v_mul_f32_e32 v143, v143, v199
	v_cvt_pk_bf16_f32 v176, v128, v129
	v_cvt_pk_bf16_f32 v177, v130, v131
	v_cvt_pk_bf16_f32 v178, v132, v133
	v_cvt_pk_bf16_f32 v179, v134, v135
	v_cvt_pk_bf16_f32 v180, v136, v137
	v_cvt_pk_bf16_f32 v181, v138, v139
	v_cvt_pk_bf16_f32 v182, v140, v141
	v_cvt_pk_bf16_f32 v183, v142, v143
	global_store_dwordx2 v234, v[176:177], s[42:43]
	global_store_dwordx2 v235, v[178:179], s[42:43]
	global_store_dwordx2 v236, v[180:181], s[42:43]
	global_store_dwordx2 v237, v[182:183], s[42:43]
	s_add_u32 s42, s42, 0x10000
	s_addc_u32 s43, s43, 0
	s_cmp_eq_u32 s52, 1
	s_cbranch_scc1 .Ls3_last
	s_add_u32 s48, s48, 0xc000
	s_addc_u32 s49, s49, 0
	s_add_u32 s28, s28, 0xc000
	s_addc_u32 s29, s29, 0
	s_add_u32 s30, s30, 0xc000
	s_addc_u32 s31, s31, 0
	s_add_u32 s34, s34, 0x2a000
	s_addc_u32 s35, s35, 0
	s_add_u32 s36, s36, 0x6000
	s_addc_u32 s37, s37, 0
	s_add_u32 s38, s38, 0x6000
	s_addc_u32 s39, s39, 0
	s_add_u32 s40, s40, 0x400
	s_addc_u32 s41, s41, 0
	global_load_dwordx4 v[80:83], v144, s[48:49] offset:0
	global_load_dwordx4 v[84:87], v144, s[48:49] offset:16
	global_load_dwordx4 v[88:91], v144, s[48:49] offset:32
	global_load_dwordx4 v[92:95], v144, s[48:49] offset:48
	global_load_dwordx4 v[128:131], v12, s[28:29]
	global_load_dwordx4 v[132:135], v12, s[28:29] offset:3072
	global_load_dwordx4 v[136:139], v12, s[30:31]
	global_load_dwordx4 v[140:143], v12, s[30:31] offset:3072
	global_load_dwordx2 v[176:177], v192, s[34:35]
	global_load_dwordx2 v[178:179], v193, s[34:35]
	global_load_dwordx2 v[180:181], v194, s[34:35]
	global_load_dwordx2 v[182:183], v195, s[34:35]
	global_load_dwordx2 v[210:211], v13, s[36:37]
	global_load_dwordx2 v[212:213], v13, s[36:37] offset:1536
	global_load_dwordx2 v[214:215], v13, s[38:39]
	global_load_dwordx2 v[216:217], v13, s[38:39] offset:1536
	global_load_dword v226, v15, s[40:41]
	global_load_dword v227, v15, s[40:41] offset:64
	global_load_dword v228, v15, s[40:41] offset:128
	global_load_dword v229, v15, s[40:41] offset:192
	s_waitcnt vmcnt(24)
	s_branch .Ls3_go
.Ls3_last:
	s_waitcnt vmcnt(4)
.Ls3_go:
	v_mfma_f32_16x16x4_f32 v[112:115], v96, v16, 0
	v_mfma_f32_16x16x4_f32 v[116:119], v96, v32, 0
	v_mfma_f32_16x16x4_f32 v[120:123], v96, v48, 0
	v_mfma_f32_16x16x4_f32 v[124:127], v96, v64, 0
	v_mfma_f32_16x16x4_f32 v[112:115], v97, v17, v[112:115]
	v_mfma_f32_16x16x4_f32 v[116:119], v97, v33, v[116:119]
	v_mfma_f32_16x16x4_f32 v[120:123], v97, v49, v[120:123]
	v_mfma_f32_16x16x4_f32 v[124:127], v97, v65, v[124:127]
	v_mfma_f32_16x16x4_f32 v[112:115], v98, v18, v[112:115]
	v_mfma_f32_16x16x4_f32 v[116:119], v98, v34, v[116:119]
	v_mfma_f32_16x16x4_f32 v[120:123], v98, v50, v[120:123]
	v_mfma_f32_16x16x4_f32 v[124:127], v98, v66, v[124:127]
	v_mfma_f32_16x16x4_f32 v[112:115], v99, v19, v[112:115]
	v_mfma_f32_16x16x4_f32 v[116:119], v99, v35, v[116:119]
	v_mfma_f32_16x16x4_f32 v[120:123], v99, v51, v[120:123]
	v_mfma_f32_16x16x4_f32 v[124:127], v99, v67, v[124:127]
	v_mfma_f32_16x16x4_f32 v[112:115], v100, v20, v[112:115]
	v_mfma_f32_16x16x4_f32 v[116:119], v100, v36, v[116:119]
	v_mfma_f32_16x16x4_f32 v[120:123], v100, v52, v[120:123]
	v_mfma_f32_16x16x4_f32 v[124:127], v100, v68, v[124:127]
	v_mfma_f32_16x16x4_f32 v[112:115], v101, v21, v[112:115]
	v_mfma_f32_16x16x4_f32 v[116:119], v101, v37, v[116:119]
	v_mfma_f32_16x16x4_f32 v[120:123], v101, v53, v[120:123]
	v_mfma_f32_16x16x4_f32 v[124:127], v101, v69, v[124:127]
	v_mfma_f32_16x16x4_f32 v[112:115], v102, v22, v[112:115]
; __device__ __forceinline__ float row16_sum(float v) { v += __shfl_xor(v, 1); v += __shfl_xor(v, 2); v += __shfl_xor(v, 4); v += __shfl_xor(v, 8); return v; }
; __device__ __forceinline__ void phase_scan3(const Params& p, const Lt& lt, unsigned char* lds) {
;     ...
;             for (int ks = 0; ks < 16; ++ks)
; #pragma unroll
;                 for (int ti = 0; ti < 4; ++ti) acc[ti] = __builtin_amdgcn_mfma_f32_16x16x4f32(av[ks], bv[ti][ks], acc[ti], 0, 0, 0);
; __device__ __forceinline__ void phase_finalize(const Params& p, const Lt& lt, int l) {
;     ...
;             const f32x4 y = *(const f32x4*)(yraw + (size_t)t * RW + c);
;             const float m = row16_sum(y[0] + y[1] + y[2] + y[3]) * (1.0f / 64);
;             const f32x4 d = y - m;
;             const float var = row16_sum(d[0] * d[0] + d[1] * d[1] + d[2] * d[2] + d[3] * d[3]) * (1.0f / 64);
	v_mfma_f32_16x16x4_f32 v[116:119], v102, v38, v[116:119]
	v_mfma_f32_16x16x4_f32 v[120:123], v102, v54, v[120:123]
	v_mfma_f32_16x16x4_f32 v[124:127], v102, v70, v[124:127]
	v_mfma_f32_16x16x4_f32 v[112:115], v103, v23, v[112:115]
	v_mfma_f32_16x16x4_f32 v[116:119], v103, v39, v[116:119]
	v_mfma_f32_16x16x4_f32 v[120:123], v103, v55, v[120:123]
	v_mfma_f32_16x16x4_f32 v[124:127], v103, v71, v[124:127]
	v_mfma_f32_16x16x4_f32 v[112:115], v104, v24, v[112:115]
	v_mfma_f32_16x16x4_f32 v[116:119], v104, v40, v[116:119]
	v_mfma_f32_16x16x4_f32 v[120:123], v104, v56, v[120:123]
	v_mfma_f32_16x16x4_f32 v[124:127], v104, v72, v[124:127]
	v_mfma_f32_16x16x4_f32 v[112:115], v105, v25, v[112:115]
	v_mfma_f32_16x16x4_f32 v[116:119], v105, v41, v[116:119]
	v_mfma_f32_16x16x4_f32 v[120:123], v105, v57, v[120:123]
	v_mfma_f32_16x16x4_f32 v[124:127], v105, v73, v[124:127]
	v_mfma_f32_16x16x4_f32 v[112:115], v106, v26, v[112:115]
	v_mfma_f32_16x16x4_f32 v[116:119], v106, v42, v[116:119]
	v_mfma_f32_16x16x4_f32 v[120:123], v106, v58, v[120:123]
	v_mfma_f32_16x16x4_f32 v[124:127], v106, v74, v[124:127]
	v_mfma_f32_16x16x4_f32 v[112:115], v107, v27, v[112:115]
	v_mfma_f32_16x16x4_f32 v[116:119], v107, v43, v[116:119]
	v_mfma_f32_16x16x4_f32 v[120:123], v107, v59, v[120:123]
	v_mfma_f32_16x16x4_f32 v[124:127], v107, v75, v[124:127]
	v_mfma_f32_16x16x4_f32 v[112:115], v108, v28, v[112:115]
	v_mfma_f32_16x16x4_f32 v[116:119], v108, v44, v[116:119]
	v_mfma_f32_16x16x4_f32 v[120:123], v108, v60, v[120:123]
	v_mfma_f32_16x16x4_f32 v[124:127], v108, v76, v[124:127]
	v_mfma_f32_16x16x4_f32 v[112:115], v109, v29, v[112:115]
	v_mfma_f32_16x16x4_f32 v[116:119], v109, v45, v[116:119]
	v_mfma_f32_16x16x4_f32 v[120:123], v109, v61, v[120:123]
	v_mfma_f32_16x16x4_f32 v[124:127], v109, v77, v[124:127]
	v_mfma_f32_16x16x4_f32 v[112:115], v110, v30, v[112:115]
	v_mfma_f32_16x16x4_f32 v[116:119], v110, v46, v[116:119]
	v_mfma_f32_16x16x4_f32 v[120:123], v110, v62, v[120:123]
	v_mfma_f32_16x16x4_f32 v[124:127], v110, v78, v[124:127]
	v_mfma_f32_16x16x4_f32 v[112:115], v111, v31, v[112:115]
	v_mfma_f32_16x16x4_f32 v[116:119], v111, v47, v[116:119]
	v_mfma_f32_16x16x4_f32 v[120:123], v111, v63, v[120:123]
	v_mfma_f32_16x16x4_f32 v[124:127], v111, v79, v[124:127]
	s_nop 9
	v_add_f32_e32 v160, v112, v160
	v_add_f32_e32 v161, v116, v161
	v_add_f32_e32 v162, v120, v162
	v_add_f32_e32 v163, v124, v163
	v_add_f32_e32 v164, v113, v164
	v_add_f32_e32 v165, v117, v165
	v_add_f32_e32 v166, v121, v166
	v_add_f32_e32 v167, v125, v167
	v_add_f32_e32 v168, v114, v168
	v_add_f32_e32 v169, v118, v169
	v_add_f32_e32 v170, v122, v170
	v_add_f32_e32 v171, v126, v171
	v_add_f32_e32 v172, v115, v172
	v_add_f32_e32 v173, v119, v173
	v_add_f32_e32 v174, v123, v174
	v_add_f32_e32 v175, v127, v175
	v_add_f32_e32 v146, v160, v161
	v_add_f32_e32 v147, v164, v165
	v_add_f32_e32 v148, v168, v169
	v_add_f32_e32 v149, v172, v173
	v_add_f32_e32 v146, v162, v146
	v_add_f32_e32 v147, v166, v147
	v_add_f32_e32 v148, v170, v148
	v_add_f32_e32 v149, v174, v149
	v_add_f32_e32 v146, v163, v146
	v_add_f32_e32 v147, v167, v147
	v_add_f32_e32 v148, v171, v148
	v_add_f32_e32 v149, v175, v149
	v_add_f32_dpp v146, v146, v146 quad_perm:[1,0,3,2] row_mask:0xf bank_mask:0xf
	v_add_f32_dpp v147, v147, v147 quad_perm:[1,0,3,2] row_mask:0xf bank_mask:0xf
	v_add_f32_dpp v148, v148, v148 quad_perm:[1,0,3,2] row_mask:0xf bank_mask:0xf
	v_add_f32_dpp v149, v149, v149 quad_perm:[1,0,3,2] row_mask:0xf bank_mask:0xf
	v_add_f32_dpp v146, v146, v146 quad_perm:[2,3,0,1] row_mask:0xf bank_mask:0xf
	v_add_f32_dpp v147, v147, v147 quad_perm:[2,3,0,1] row_mask:0xf bank_mask:0xf
	v_add_f32_dpp v148, v148, v148 quad_perm:[2,3,0,1] row_mask:0xf bank_mask:0xf
	v_add_f32_dpp v149, v149, v149 quad_perm:[2,3,0,1] row_mask:0xf bank_mask:0xf
	v_add_f32_dpp v146, v146, v146 row_half_mirror row_mask:0xf bank_mask:0xf
	v_add_f32_dpp v147, v147, v147 row_half_mirror row_mask:0xf bank_mask:0xf
	v_add_f32_dpp v148, v148, v148 row_half_mirror row_mask:0xf bank_mask:0xf
	v_add_f32_dpp v149, v149, v149 row_half_mirror row_mask:0xf bank_mask:0xf
	v_add_f32_dpp v146, v146, v146 row_mirror row_mask:0xf bank_mask:0xf
	v_add_f32_dpp v147, v147, v147 row_mirror row_mask:0xf bank_mask:0xf
	v_add_f32_dpp v148, v148, v148 row_mirror row_mask:0xf bank_mask:0xf
	v_add_f32_dpp v149, v149, v149 row_mirror row_mask:0xf bank_mask:0xf
	v_fmamk_f32 v160, v146, 0xbc800000, v160
	v_fmamk_f32 v161, v146, 0xbc800000, v161
	v_fmamk_f32 v162, v146, 0xbc800000, v162
	v_fmamk_f32 v163, v146, 0xbc800000, v163
	v_fmamk_f32 v164, v147, 0xbc800000, v164
	v_fmamk_f32 v165, v147, 0xbc800000, v165
	v_fmamk_f32 v166, v147, 0xbc800000, v166
	v_fmamk_f32 v167, v147, 0xbc800000, v167
	v_fmamk_f32 v168, v148, 0xbc800000, v168
	v_fmamk_f32 v169, v148, 0xbc800000, v169
	v_fmamk_f32 v170, v148, 0xbc800000, v170
	v_fmamk_f32 v171, v148, 0xbc800000, v171
	v_fmamk_f32 v172, v149, 0xbc800000, v172
	v_fmamk_f32 v173, v149, 0xbc800000, v173
	v_fmamk_f32 v174, v149, 0xbc800000, v174
	v_fmamk_f32 v175, v149, 0xbc800000, v175
	v_mul_f32_e32 v154, v160, v160
	v_mul_f32_e32 v155, v161, v161
	v_mul_f32_e32 v156, v164, v164
	v_mul_f32_e32 v157, v165, v165
	v_mul_f32_e32 v158, v168, v168
	v_mul_f32_e32 v159, v169, v169
	v_mul_f32_e32 v198, v172, v172
	v_mul_f32_e32 v199, v173, v173
	v_add_f32_e32 v150, v154, v155
	v_add_f32_e32 v151, v156, v157
	v_add_f32_e32 v152, v158, v159
	v_add_f32_e32 v153, v198, v199
	v_mul_f32_e32 v154, v162, v162
	v_mul_f32_e32 v156, v166, v166
	v_mul_f32_e32 v158, v170, v170
	v_mul_f32_e32 v198, v174, v174
	v_mul_f32_e32 v155, v163, v163
	v_mul_f32_e32 v157, v167, v167
; __device__ __forceinline__ unsigned cvt_pk_bf16(float lo, float hi) { const f32x2 v = {lo, hi}; return __builtin_bit_cast(unsigned, __builtin_convertvector(v, bf16x2_t)); }
; __device__ __forceinline__ float row16_sum(float v) { v += __shfl_xor(v, 1); v += __shfl_xor(v, 2); v += __shfl_xor(v, 4); v += __shfl_xor(v, 8); return v; }
; __device__ __forceinline__ f32x4 ld_bf4(const bf16_t* q) { const u32x2 u = *(const u32x2*)q; return (f32x4){bflo(u.x), bfhi(u.x), bflo(u.y), bfhi(u.y)}; }
; __device__ __forceinline__ void phase_scan3(const Params& p, const Lt& lt, unsigned char* lds) {
;     ...
;     for (int it = w * G + lt.bid; it < NH * NSEG; it += 8 * G) {
; __device__ __forceinline__ void phase_finalize(const Params& p, const Lt& lt, int l) {
;     ...
;             const f32x4 y = *(const f32x4*)(yraw + (size_t)t * RW + c);
;             const float m = row16_sum(y[0] + y[1] + y[2] + y[3]) * (1.0f / 64);
;             const f32x4 d = y - m;
;             const float var = row16_sum(d[0] * d[0] + d[1] * d[1] + d[2] * d[2] + d[3] * d[3]) * (1.0f / 64);
;             const float rs = rsqrtf(var + GN_EPS);
;             const f32x4 g4 = *(const f32x4*)(lg + c), b4 = *(const f32x4*)(lb + c), v4 = ld_bf4((const bf16_t*)(opnd + (size_t)t * OPTB + h * OPB + 640 + cc * 2)), gt = ld_bf4((const bf16_t*)gate + (size_t)t * RW + c);
;             const float bo = bonus[(size_t)t * 16 + h];
;             const f32x4 o = (d * rs * g4 + b4 + v4 * bo) * gt;
;             u32x2 pk; pk.x = cvt_pk_bf16(o[0], o[1]); pk.y = cvt_pk_bf16(o[2], o[3]);
;             *(u32x2*)(mix + (size_t)t * DM + c) = pk;
	v_mul_f32_e32 v159, v171, v171
	v_mul_f32_e32 v199, v175, v175
	v_add_f32_e32 v150, v154, v150
	v_add_f32_e32 v151, v156, v151
	v_add_f32_e32 v152, v158, v152
	v_add_f32_e32 v153, v198, v153
	v_add_f32_e32 v150, v155, v150
	v_add_f32_e32 v151, v157, v151
	v_add_f32_e32 v152, v159, v152
	v_add_f32_e32 v153, v199, v153
	v_add_f32_dpp v150, v150, v150 quad_perm:[1,0,3,2] row_mask:0xf bank_mask:0xf
	v_add_f32_dpp v151, v151, v151 quad_perm:[1,0,3,2] row_mask:0xf bank_mask:0xf
	v_add_f32_dpp v152, v152, v152 quad_perm:[1,0,3,2] row_mask:0xf bank_mask:0xf
	v_add_f32_dpp v153, v153, v153 quad_perm:[1,0,3,2] row_mask:0xf bank_mask:0xf
	v_add_f32_dpp v150, v150, v150 quad_perm:[2,3,0,1] row_mask:0xf bank_mask:0xf
	v_add_f32_dpp v151, v151, v151 quad_perm:[2,3,0,1] row_mask:0xf bank_mask:0xf
	v_add_f32_dpp v152, v152, v152 quad_perm:[2,3,0,1] row_mask:0xf bank_mask:0xf
	v_add_f32_dpp v153, v153, v153 quad_perm:[2,3,0,1] row_mask:0xf bank_mask:0xf
	v_add_f32_dpp v150, v150, v150 row_half_mirror row_mask:0xf bank_mask:0xf
	v_add_f32_dpp v151, v151, v151 row_half_mirror row_mask:0xf bank_mask:0xf
	v_add_f32_dpp v152, v152, v152 row_half_mirror row_mask:0xf bank_mask:0xf
	v_add_f32_dpp v153, v153, v153 row_half_mirror row_mask:0xf bank_mask:0xf
	v_add_f32_dpp v150, v150, v150 row_mirror row_mask:0xf bank_mask:0xf
	v_add_f32_dpp v151, v151, v151 row_mirror row_mask:0xf bank_mask:0xf
	v_add_f32_dpp v152, v152, v152 row_mirror row_mask:0xf bank_mask:0xf
	v_add_f32_dpp v153, v153, v153 row_mirror row_mask:0xf bank_mask:0xf
	v_fmamk_f32 v150, v150, 0x3c800000, v196
	v_fmamk_f32 v151, v151, 0x3c800000, v196
	v_fmamk_f32 v152, v152, 0x3c800000, v196
	v_fmamk_f32 v153, v153, 0x3c800000, v196
	v_rsq_f32_e32 v150, v150
	v_rsq_f32_e32 v151, v151
	v_rsq_f32_e32 v152, v152
	v_rsq_f32_e32 v153, v153
	s_nop 0
	v_mul_f32_e32 v160, v160, v150
	v_mul_f32_e32 v161, v161, v150
	v_mul_f32_e32 v162, v162, v150
	v_mul_f32_e32 v163, v163, v150
	v_mul_f32_e32 v164, v164, v151
	v_mul_f32_e32 v165, v165, v151
	v_mul_f32_e32 v166, v166, v151
	v_mul_f32_e32 v167, v167, v151
	v_mul_f32_e32 v168, v168, v152
	v_mul_f32_e32 v169, v169, v152
	v_mul_f32_e32 v170, v170, v152
	v_mul_f32_e32 v171, v171, v152
	v_mul_f32_e32 v172, v172, v153
	v_mul_f32_e32 v173, v173, v153
	v_mul_f32_e32 v174, v174, v153
	v_mul_f32_e32 v175, v175, v153
	v_fma_f32 v160, v4, v160, v8
	v_fma_f32 v161, v5, v161, v9
	v_fma_f32 v162, v6, v162, v10
	v_fma_f32 v163, v7, v163, v11
	v_fma_f32 v164, v4, v164, v8
	v_fma_f32 v165, v5, v165, v9
	v_fma_f32 v166, v6, v166, v10
	v_fma_f32 v167, v7, v167, v11
	v_fma_f32 v168, v4, v168, v8
	v_fma_f32 v169, v5, v169, v9
	v_fma_f32 v170, v6, v170, v10
	v_fma_f32 v171, v7, v171, v11
	v_fma_f32 v172, v4, v172, v8
	v_fma_f32 v173, v5, v173, v9
	v_fma_f32 v174, v6, v174, v10
	v_fma_f32 v175, v7, v175, v11
	v_lshlrev_b32_e32 v154, 16, v184
	v_and_b32_e32 v155, 0xffff0000, v184
	v_lshlrev_b32_e32 v156, 16, v185
	v_and_b32_e32 v157, 0xffff0000, v185
	v_fma_f32 v160, v230, v154, v160
	v_fma_f32 v161, v230, v155, v161
	v_fma_f32 v162, v230, v156, v162
	v_fma_f32 v163, v230, v157, v163
	v_lshlrev_b32_e32 v158, 16, v186
	v_and_b32_e32 v159, 0xffff0000, v186
	v_lshlrev_b32_e32 v198, 16, v187
	v_and_b32_e32 v199, 0xffff0000, v187
	v_fma_f32 v164, v231, v158, v164
	v_fma_f32 v165, v231, v159, v165
	v_fma_f32 v166, v231, v198, v166
	v_fma_f32 v167, v231, v199, v167
	v_lshlrev_b32_e32 v154, 16, v188
	v_and_b32_e32 v155, 0xffff0000, v188
	v_lshlrev_b32_e32 v156, 16, v189
	v_and_b32_e32 v157, 0xffff0000, v189
	v_fma_f32 v168, v232, v154, v168
	v_fma_f32 v169, v232, v155, v169
	v_fma_f32 v170, v232, v156, v170
	v_fma_f32 v171, v232, v157, v171
	v_lshlrev_b32_e32 v158, 16, v190
	v_and_b32_e32 v159, 0xffff0000, v190
	v_lshlrev_b32_e32 v198, 16, v191
	v_and_b32_e32 v199, 0xffff0000, v191
	v_fma_f32 v172, v233, v158, v172
	v_fma_f32 v173, v233, v159, v173
	v_fma_f32 v174, v233, v198, v174
	v_fma_f32 v175, v233, v199, v175
	v_lshlrev_b32_e32 v154, 16, v218
	v_and_b32_e32 v155, 0xffff0000, v218
	v_lshlrev_b32_e32 v156, 16, v219
	v_and_b32_e32 v157, 0xffff0000, v219
	v_mul_f32_e32 v160, v160, v154
	v_mul_f32_e32 v161, v161, v155
	v_mul_f32_e32 v162, v162, v156
	v_mul_f32_e32 v163, v163, v157
	v_lshlrev_b32_e32 v158, 16, v220
	v_and_b32_e32 v159, 0xffff0000, v220
	v_lshlrev_b32_e32 v198, 16, v221
	v_and_b32_e32 v199, 0xffff0000, v221
	v_mul_f32_e32 v164, v164, v158
	v_mul_f32_e32 v165, v165, v159
	v_mul_f32_e32 v166, v166, v198
	v_mul_f32_e32 v167, v167, v199
	v_lshlrev_b32_e32 v154, 16, v222
	v_and_b32_e32 v155, 0xffff0000, v222
	v_lshlrev_b32_e32 v156, 16, v223
	v_and_b32_e32 v157, 0xffff0000, v223
	v_mul_f32_e32 v168, v168, v154
	v_mul_f32_e32 v169, v169, v155
	v_mul_f32_e32 v170, v170, v156
	v_mul_f32_e32 v171, v171, v157
	v_lshlrev_b32_e32 v158, 16, v224
	v_and_b32_e32 v159, 0xffff0000, v224
	v_lshlrev_b32_e32 v198, 16, v225
	v_and_b32_e32 v199, 0xffff0000, v225
	v_mul_f32_e32 v172, v172, v158
	v_mul_f32_e32 v173, v173, v159
	v_mul_f32_e32 v174, v174, v198
	v_mul_f32_e32 v175, v175, v199
	v_cvt_pk_bf16_f32 v184, v160, v161
	v_cvt_pk_bf16_f32 v185, v162, v163
	v_cvt_pk_bf16_f32 v186, v164, v165
	v_cvt_pk_bf16_f32 v187, v166, v167
	v_cvt_pk_bf16_f32 v188, v168, v169
	v_cvt_pk_bf16_f32 v189, v170, v171
	v_cvt_pk_bf16_f32 v190, v172, v173
	v_cvt_pk_bf16_f32 v191, v174, v175
	global_store_dwordx2 v234, v[184:185], s[42:43]
	global_store_dwordx2 v235, v[186:187], s[42:43]
	global_store_dwordx2 v236, v[188:189], s[42:43]
	global_store_dwordx2 v237, v[190:191], s[42:43]
	s_add_u32 s42, s42, 0x10000
	s_addc_u32 s43, s43, 0
	s_add_u32 s52, s52, 1
	s_cmp_lt_u32 s52, 2
	s_cbranch_scc1 .Ls3_trip
	s_add_i32 s0, s0, s84
	s_cmpk_gt_i32 s0, 0x5ff
	s_cbranch_scc0 .LBB0_137
	s_branch .LBB0_140
; __device__ __forceinline__ void phase_finalize(const Params& p, const Lt& lt, int l) {
;     ...
;     const float* lg = p.in[12] + l * RW; const float* lb = p.in[13] + l * RW; const float* ang = p.in[15] + l * RW;
;     bf16_t* mix = (bf16_t*)(p.ws + WS_MIX);
;     for (int t = lt.bid * 8 + w; t < SEQ; t += gridDim.x * 8) {
;         const f32x4 sq = *(const f32x4*)(ssqa + (size_t)t * 4);
;         const float ra = rsqrtf((sq[0] + sq[1] + sq[2] + sq[3]) * (1.0f / RW) + NORM_EPS);
;     ...
;             const f32x4 oa = *(const f32x4*)(oraw + (size_t)t * RW + c) * ra * *(const f32x4*)(ang + c);
.Lfin_attn:
	s_lshr_b32 s1, s0, 8
	s_sub_u32 s1, s1, 6
	s_lshl_b32 s4, s86, 5
	s_lshl_b32 s1, s1, 4
	s_add_u32 s4, s4, s1
	s_lshl_b32 s5, s4, 4
	s_add_u32 s28, s62, 0x2d780000
	s_addc_u32 s29, s63, 0
	s_add_u32 s28, s28, s5
	s_addc_u32 s29, s29, 0
	s_mul_i32 s5, s4, 0xc00
	s_add_u32 s30, s62, 0x2bf80000
	s_addc_u32 s31, s63, 0
	s_add_u32 s30, s30, s5
	s_addc_u32 s31, s31, 0
	s_lshl_b32 s5, s4, 12
	s_add_u32 s34, s62, 0x1cf00000
	s_addc_u32 s35, s63, 0
	s_add_u32 s34, s34, s5
	s_addc_u32 s35, s35, 0
	v_readlane_b32 s4, v254, 1
	s_mul_i32 s4, s4, 0xc00
	v_readlane_b32 s36, v253, 41
	v_readlane_b32 s37, v253, 42
	s_add_u32 s36, s36, s4
	s_addc_u32 s37, s37, 0
	v_and_b32_e32 v2, 63, v245
	v_lshlrev_b32_e32 v0, 4, v2
	v_lshlrev_b32_e32 v1, 3, v2
	global_load_dwordx4 v[4:7], v0, s[36:37] offset:0
	global_load_dwordx4 v[8:11], v0, s[36:37] offset:1024
	global_load_dwordx4 v[12:15], v0, s[36:37] offset:2048
	s_mov_b32 s1, 0
; __device__ __forceinline__ unsigned cvt_pk_bf16(float lo, float hi) { const f32x2 v = {lo, hi}; return __builtin_bit_cast(unsigned, __builtin_convertvector(v, bf16x2_t)); }
; __device__ __forceinline__ void phase_finalize(const Params& p, const Lt& lt, int l) {
;     ...
;         const f32x4 sq = *(const f32x4*)(ssqa + (size_t)t * 4);
;         const float ra = rsqrtf((sq[0] + sq[1] + sq[2] + sq[3]) * (1.0f / RW) + NORM_EPS);
;     ...
;             const f32x4 oa = *(const f32x4*)(oraw + (size_t)t * RW + c) * ra * *(const f32x4*)(ang + c);
;             u32x2 pa; pa.x = cvt_pk_bf16(oa[0], oa[1]); pa.y = cvt_pk_bf16(oa[2], oa[3]);
;             *(u32x2*)(mix + (size_t)t * DM + RW + c) = pa;
.Lfin_attn_loop:
	global_load_dwordx4 v[16:19], v3, s[28:29] offset:0
	global_load_dwordx4 v[32:35], v0, s[30:31] offset:0
	global_load_dwordx4 v[36:39], v0, s[30:31] offset:1024
	global_load_dwordx4 v[40:43], v0, s[30:31] offset:2048
	s_add_u32 s30, s30, 0xc00
	s_addc_u32 s31, s31, 0
	global_load_dwordx4 v[20:23], v3, s[28:29] offset:16
	global_load_dwordx4 v[44:47], v0, s[30:31] offset:0
	global_load_dwordx4 v[48:51], v0, s[30:31] offset:1024
	global_load_dwordx4 v[52:55], v0, s[30:31] offset:2048
	s_add_u32 s30, s30, 0xc00
	s_addc_u32 s31, s31, 0
	global_load_dwordx4 v[24:27], v3, s[28:29] offset:32
	global_load_dwordx4 v[56:59], v0, s[30:31] offset:0
	global_load_dwordx4 v[60:63], v0, s[30:31] offset:1024
	global_load_dwordx4 v[64:67], v0, s[30:31] offset:2048
	s_add_u32 s30, s30, 0xc00
	s_addc_u32 s31, s31, 0
	global_load_dwordx4 v[28:31], v3, s[28:29] offset:48
	global_load_dwordx4 v[68:71], v0, s[30:31] offset:0
	global_load_dwordx4 v[72:75], v0, s[30:31] offset:1024
	global_load_dwordx4 v[76:79], v0, s[30:31] offset:2048
	s_add_u32 s30, s30, 0xc00
	s_addc_u32 s31, s31, 0
	s_add_u32 s28, s28, 64
	s_addc_u32 s29, s29, 0
	s_waitcnt vmcnt(12)
	v_add_f32_e32 v16, v16, v17
	v_add_f32_e32 v16, v16, v18
	v_add_f32_e32 v16, v16, v19
	v_fmamk_f32 v16, v16, 0x3aaaaaab, v197
	v_rsq_f32_e32 v16, v16
	s_nop 0
	v_mul_f32_e32 v32, v16, v32
	v_mul_f32_e32 v33, v16, v33
	v_mul_f32_e32 v34, v16, v34
	v_mul_f32_e32 v35, v16, v35
	v_mul_f32_e32 v36, v16, v36
	v_mul_f32_e32 v37, v16, v37
	v_mul_f32_e32 v38, v16, v38
	v_mul_f32_e32 v39, v16, v39
	v_mul_f32_e32 v40, v16, v40
	v_mul_f32_e32 v41, v16, v41
	v_mul_f32_e32 v42, v16, v42
	v_mul_f32_e32 v43, v16, v43
	v_mul_f32_e32 v32, v32, v4
	v_mul_f32_e32 v33, v33, v5
	v_mul_f32_e32 v34, v34, v6
	v_mul_f32_e32 v35, v35, v7
	v_mul_f32_e32 v36, v36, v8
	v_mul_f32_e32 v37, v37, v9
	v_mul_f32_e32 v38, v38, v10
	v_mul_f32_e32 v39, v39, v11
	v_mul_f32_e32 v40, v40, v12
	v_mul_f32_e32 v41, v41, v13
	v_mul_f32_e32 v42, v42, v14
	v_mul_f32_e32 v43, v43, v15
	v_cvt_pk_bf16_f32 v32, v32, v33
	v_cvt_pk_bf16_f32 v33, v34, v35
	v_cvt_pk_bf16_f32 v36, v36, v37
	v_cvt_pk_bf16_f32 v37, v38, v39
	v_cvt_pk_bf16_f32 v40, v40, v41
	v_cvt_pk_bf16_f32 v41, v42, v43
	s_waitcnt vmcnt(8)
	v_add_f32_e32 v20, v20, v21
	v_add_f32_e32 v20, v20, v22
	v_add_f32_e32 v20, v20, v23
	v_fmamk_f32 v20, v20, 0x3aaaaaab, v197
	v_rsq_f32_e32 v20, v20
	s_nop 0
	v_mul_f32_e32 v44, v20, v44
	v_mul_f32_e32 v45, v20, v45
	v_mul_f32_e32 v46, v20, v46
	v_mul_f32_e32 v47, v20, v47
	v_mul_f32_e32 v48, v20, v48
	v_mul_f32_e32 v49, v20, v49
	v_mul_f32_e32 v50, v20, v50
	v_mul_f32_e32 v51, v20, v51
	v_mul_f32_e32 v52, v20, v52
	v_mul_f32_e32 v53, v20, v53
	v_mul_f32_e32 v54, v20, v54
	v_mul_f32_e32 v55, v20, v55
	v_mul_f32_e32 v44, v44, v4
	v_mul_f32_e32 v45, v45, v5
	v_mul_f32_e32 v46, v46, v6
	v_mul_f32_e32 v47, v47, v7
	v_mul_f32_e32 v48, v48, v8
	v_mul_f32_e32 v49, v49, v9
	v_mul_f32_e32 v50, v50, v10
	v_mul_f32_e32 v51, v51, v11
	v_mul_f32_e32 v52, v52, v12
	v_mul_f32_e32 v53, v53, v13
	v_mul_f32_e32 v54, v54, v14
	v_mul_f32_e32 v55, v55, v15
	v_cvt_pk_bf16_f32 v44, v44, v45
	v_cvt_pk_bf16_f32 v45, v46, v47
	v_cvt_pk_bf16_f32 v48, v48, v49
	v_cvt_pk_bf16_f32 v49, v50, v51
	v_cvt_pk_bf16_f32 v52, v52, v53
	v_cvt_pk_bf16_f32 v53, v54, v55
	s_waitcnt vmcnt(4)
	v_add_f32_e32 v24, v24, v25
	v_add_f32_e32 v24, v24, v26
	v_add_f32_e32 v24, v24, v27
	v_fmamk_f32 v24, v24, 0x3aaaaaab, v197
	v_rsq_f32_e32 v24, v24
	s_nop 0
	v_mul_f32_e32 v56, v24, v56
	v_mul_f32_e32 v57, v24, v57
	v_mul_f32_e32 v58, v24, v58
	v_mul_f32_e32 v59, v24, v59
	v_mul_f32_e32 v60, v24, v60
	v_mul_f32_e32 v61, v24, v61
	v_mul_f32_e32 v62, v24, v62
	v_mul_f32_e32 v63, v24, v63
	v_mul_f32_e32 v64, v24, v64
	v_mul_f32_e32 v65, v24, v65
	v_mul_f32_e32 v66, v24, v66
	v_mul_f32_e32 v67, v24, v67
	v_mul_f32_e32 v56, v56, v4
	v_mul_f32_e32 v57, v57, v5
	v_mul_f32_e32 v58, v58, v6
	v_mul_f32_e32 v59, v59, v7
	v_mul_f32_e32 v60, v60, v8
	v_mul_f32_e32 v61, v61, v9
	v_mul_f32_e32 v62, v62, v10
	v_mul_f32_e32 v63, v63, v11
	v_mul_f32_e32 v64, v64, v12
	v_mul_f32_e32 v65, v65, v13
	v_mul_f32_e32 v66, v66, v14
	v_mul_f32_e32 v67, v67, v15
	v_cvt_pk_bf16_f32 v56, v56, v57
	v_cvt_pk_bf16_f32 v57, v58, v59
	v_cvt_pk_bf16_f32 v60, v60, v61
	v_cvt_pk_bf16_f32 v61, v62, v63
	v_cvt_pk_bf16_f32 v64, v64, v65
	v_cvt_pk_bf16_f32 v65, v66, v67
	s_waitcnt vmcnt(0)
	v_add_f32_e32 v28, v28, v29
	v_add_f32_e32 v28, v28, v30
	v_add_f32_e32 v28, v28, v31
	v_fmamk_f32 v28, v28, 0x3aaaaaab, v197
	v_rsq_f32_e32 v28, v28
	s_nop 0
	v_mul_f32_e32 v68, v28, v68
	v_mul_f32_e32 v69, v28, v69
	v_mul_f32_e32 v70, v28, v70
	v_mul_f32_e32 v71, v28, v71
	v_mul_f32_e32 v72, v28, v72
	v_mul_f32_e32 v73, v28, v73
	v_mul_f32_e32 v74, v28, v74
	v_mul_f32_e32 v75, v28, v75
	v_mul_f32_e32 v76, v28, v76
	v_mul_f32_e32 v77, v28, v77
	v_mul_f32_e32 v78, v28, v78
	v_mul_f32_e32 v79, v28, v79
	v_mul_f32_e32 v68, v68, v4
	v_mul_f32_e32 v69, v69, v5
	v_mul_f32_e32 v70, v70, v6
	v_mul_f32_e32 v71, v71, v7
	v_mul_f32_e32 v72, v72, v8
	v_mul_f32_e32 v73, v73, v9
	v_mul_f32_e32 v74, v74, v10
	v_mul_f32_e32 v75, v75, v11
	v_mul_f32_e32 v76, v76, v12
	v_mul_f32_e32 v77, v77, v13
	v_mul_f32_e32 v78, v78, v14
	v_mul_f32_e32 v79, v79, v15
	v_cvt_pk_bf16_f32 v68, v68, v69
	v_cvt_pk_bf16_f32 v69, v70, v71
	v_cvt_pk_bf16_f32 v72, v72, v73
	v_cvt_pk_bf16_f32 v73, v74, v75
	v_cvt_pk_bf16_f32 v76, v76, v77
	v_cvt_pk_bf16_f32 v77, v78, v79
	global_store_dwordx2 v1, v[32:33], s[34:35] offset:1536
	global_store_dwordx2 v1, v[36:37], s[34:35] offset:2048
	global_store_dwordx2 v1, v[40:41], s[34:35] offset:2560
	s_add_u32 s34, s34, 0x1000
	s_addc_u32 s35, s35, 0
	global_store_dwordx2 v1, v[44:45], s[34:35] offset:1536
	global_store_dwordx2 v1, v[48:49], s[34:35] offset:2048
	global_store_dwordx2 v1, v[52:53], s[34:35] offset:2560
	s_add_u32 s34, s34, 0x1000
	s_addc_u32 s35, s35, 0
	global_store_dwordx2 v1, v[56:57], s[34:35] offset:1536
	global_store_dwordx2 v1, v[60:61], s[34:35] offset:2048
	global_store_dwordx2 v1, v[64:65], s[34:35] offset:2560
	s_add_u32 s34, s34, 0x1000
	s_addc_u32 s35, s35, 0
	global_store_dwordx2 v1, v[68:69], s[34:35] offset:1536
	global_store_dwordx2 v1, v[72:73], s[34:35] offset:2048
	global_store_dwordx2 v1, v[76:77], s[34:35] offset:2560
	s_add_u32 s34, s34, 0x1000
	s_addc_u32 s35, s35, 0
	s_add_u32 s1, s1, 1
	s_cmp_lt_u32 s1, 4
	s_cbranch_scc1 .Lfin_attn_loop
